# on top of low-rank K-slice: FFN-out residual epilogue keeps up to 5 X-row loads in flight in column groups 2-4 (was 1 serialized round trip per row)
# speedup vs baseline: 1.0829x; 1.0025x over previous
.LBB0_1830:
	global_load_dwordx4 v[170:173], v[28:29], off offset:64
	global_load_dwordx4 v[180:183], v[32:33], off offset:64
	global_load_dwordx4 v[214:217], v[38:39], off offset:64
	global_load_dwordx4 v[218:221], v[48:49], off offset:64
	global_load_dwordx4 v[222:225], v[168:169], off offset:64
	s_waitcnt vmcnt(5)
	v_pk_add_f32 v[12:13], v[12:13], 1.0 op_sel_hi:[1,0]
	v_pk_add_f32 v[10:11], v[10:11], 1.0 op_sel_hi:[1,0]
	v_mov_b32_e32 v8, v18
	v_mov_b32_e32 v148, v18
	v_mov_b32_e32 v149, v9
	v_pk_mul_f32 v[174:175], v[12:13], 0.5 op_sel_hi:[1,0]
	v_pk_mul_f32 v[176:177], v[10:11], 0.5 op_sel_hi:[1,0]
	v_mov_b32_e32 v203, v19
	v_mov_b32_e32 v206, v22
	v_mov_b32_e32 v205, v23
	v_mov_b32_e32 v44, v36
	v_mov_b32_e32 v43, v37
	v_mov_b32_e32 v25, v24
	v_mov_b32_e32 v27, v26
	v_readlane_b32 s70, v255, 18
	s_and_b64 vcc, exec, s[40:41]
	s_movk_i32 s60, 0x306
	s_movk_i32 s61, 0x5a
	s_movk_i32 s62, 0xa5
	s_movk_i32 s63, 0x130
	s_movk_i32 s66, 0x22e
	s_movk_i32 s67, 0x210
	s_movk_i32 s68, 0x1000
	v_readlane_b32 s71, v255, 19
	s_waitcnt vmcnt(4)
	v_sub_f32_e32 v11, v171, v0
	v_sub_f32_e32 v10, v170, v0
	v_sub_f32_e32 v13, v173, v0
	v_sub_f32_e32 v12, v172, v0
	v_pk_mul_f32 v[12:13], v[148:149], v[12:13]
	v_pk_mul_f32 v[10:11], v[8:9], v[10:11]
	v_pk_fma_f32 v[12:13], v[150:151], v[12:13], v[154:155]
	v_pk_fma_f32 v[10:11], v[210:211], v[10:11], v[212:213]
	v_pk_fma_f32 v[12:13], v[146:147], v[174:175], v[12:13]
	v_pk_fma_f32 v[10:11], v[144:145], v[176:177], v[10:11]
	global_store_dwordx4 v[30:31], v[10:13], off offset:64
	s_nop 1
	v_mov_b32_e32 v144, v202
	v_mov_b32_e32 v145, v19
	s_waitcnt vmcnt(4)
	v_sub_f32_e32 v11, v181, v1
	v_sub_f32_e32 v10, v180, v1
	v_sub_f32_e32 v13, v183, v1
	v_sub_f32_e32 v12, v182, v1
	v_pk_mul_f32 v[12:13], v[144:145], v[12:13]
	v_pk_mul_f32 v[10:11], v[202:203], v[10:11]
	v_pk_fma_f32 v[12:13], v[150:151], v[12:13], v[154:155]
	v_pk_fma_f32 v[10:11], v[210:211], v[10:11], v[212:213]
	v_pk_fma_f32 v[12:13], v[142:143], v[174:175], v[12:13]
	v_pk_fma_f32 v[10:11], v[140:141], v[176:177], v[10:11]
	global_store_dwordx4 v[34:35], v[10:13], off offset:64
	global_load_dwordx4 v[180:183], v[166:167], off offset:64
	v_mov_b32_e32 v140, v22
	v_mov_b32_e32 v141, v207
	s_waitcnt vmcnt(5)
	v_sub_f32_e32 v11, v215, v2
	v_sub_f32_e32 v10, v214, v2
	v_sub_f32_e32 v13, v217, v2
	v_sub_f32_e32 v12, v216, v2
	v_pk_mul_f32 v[12:13], v[140:141], v[12:13]
	v_pk_mul_f32 v[10:11], v[206:207], v[10:11]
	v_pk_fma_f32 v[12:13], v[150:151], v[12:13], v[154:155]
	v_pk_fma_f32 v[10:11], v[210:211], v[10:11], v[212:213]
	v_pk_fma_f32 v[12:13], v[138:139], v[174:175], v[12:13]
	v_pk_fma_f32 v[10:11], v[136:137], v[176:177], v[10:11]
	global_store_dwordx4 v[46:47], v[10:13], off offset:64
	global_load_dwordx4 v[214:217], v[162:163], off offset:64
	v_mov_b32_e32 v136, v204
	v_mov_b32_e32 v137, v23
	s_waitcnt vmcnt(6)
	v_sub_f32_e32 v11, v219, v3
	v_sub_f32_e32 v10, v218, v3
	v_sub_f32_e32 v13, v221, v3
	v_sub_f32_e32 v12, v220, v3
	v_pk_mul_f32 v[12:13], v[136:137], v[12:13]
	v_pk_mul_f32 v[10:11], v[204:205], v[10:11]
	v_pk_fma_f32 v[12:13], v[150:151], v[12:13], v[154:155]
	v_pk_fma_f32 v[10:11], v[210:211], v[10:11], v[212:213]
	v_pk_fma_f32 v[12:13], v[134:135], v[174:175], v[12:13]
	v_pk_fma_f32 v[10:11], v[132:133], v[176:177], v[10:11]
	global_store_dwordx4 v[40:41], v[10:13], off offset:64
	global_load_dwordx4 v[218:221], v[158:159], off offset:64
	v_mov_b32_e32 v132, v36
	v_mov_b32_e32 v133, v45
	v_mov_b32_e32 v134, 0
	v_mov_b32_e32 v135, 0
	s_waitcnt vmcnt(7)
	v_sub_f32_e32 v11, v223, v4
	v_sub_f32_e32 v10, v222, v4
	v_sub_f32_e32 v13, v225, v4
	v_sub_f32_e32 v12, v224, v4
	v_pk_mul_f32 v[12:13], v[132:133], v[12:13]
	v_pk_mul_f32 v[10:11], v[44:45], v[10:11]
	v_pk_fma_f32 v[12:13], v[150:151], v[12:13], v[154:155]
	v_pk_fma_f32 v[10:11], v[210:211], v[10:11], v[212:213]
	v_pk_fma_f32 v[12:13], v[130:131], v[174:175], v[12:13]
	v_pk_fma_f32 v[10:11], v[128:129], v[176:177], v[10:11]
	global_store_dwordx4 v[164:165], v[10:13], off offset:64
	s_nop 1
	v_mov_b32_e32 v128, v42
	v_mov_b32_e32 v129, v37
	v_mov_b32_e32 v130, 0
	v_mov_b32_e32 v131, 0
	s_waitcnt vmcnt(5)
	v_sub_f32_e32 v11, v181, v5
	v_sub_f32_e32 v10, v180, v5
	v_sub_f32_e32 v13, v183, v5
	v_sub_f32_e32 v12, v182, v5
	v_pk_mul_f32 v[12:13], v[128:129], v[12:13]
	v_pk_mul_f32 v[10:11], v[42:43], v[10:11]
	v_pk_fma_f32 v[12:13], v[150:151], v[12:13], v[154:155]
	v_pk_fma_f32 v[10:11], v[210:211], v[10:11], v[212:213]
	v_pk_fma_f32 v[12:13], v[126:127], v[174:175], v[12:13]
	v_pk_fma_f32 v[10:11], v[124:125], v[176:177], v[10:11]
	global_store_dwordx4 v[160:161], v[10:13], off offset:64
	s_nop 1
	v_mov_b32_e32 v124, v24
	v_mov_b32_e32 v125, v24
	v_mov_b32_e32 v126, 1.0
	v_mov_b32_e32 v127, 1.0
	s_waitcnt vmcnt(4)
	v_sub_f32_e32 v11, v215, v6
	v_sub_f32_e32 v10, v214, v6
	v_sub_f32_e32 v13, v217, v6
	v_sub_f32_e32 v12, v216, v6
	v_pk_mul_f32 v[12:13], v[124:125], v[12:13]
	v_pk_mul_f32 v[10:11], v[24:25], v[10:11]
	v_pk_fma_f32 v[12:13], v[150:151], v[12:13], v[154:155]
	v_pk_fma_f32 v[10:11], v[210:211], v[10:11], v[212:213]
	v_pk_fma_f32 v[12:13], v[122:123], v[174:175], v[12:13]
	v_pk_fma_f32 v[10:11], v[120:121], v[176:177], v[10:11]
	global_store_dwordx4 v[156:157], v[10:13], off offset:64
	s_nop 1
	v_mov_b32_e32 v120, v26
	v_mov_b32_e32 v121, v26
	v_mov_b32_e32 v122, 1.0
	v_mov_b32_e32 v123, 1.0
	s_waitcnt vmcnt(3)
	v_sub_f32_e32 v11, v219, v7
	v_sub_f32_e32 v10, v218, v7
	v_sub_f32_e32 v13, v221, v7
	v_sub_f32_e32 v12, v220, v7
	v_pk_mul_f32 v[12:13], v[120:121], v[12:13]
	v_pk_mul_f32 v[10:11], v[26:27], v[10:11]
	v_pk_fma_f32 v[12:13], v[150:151], v[12:13], v[154:155]
	v_pk_fma_f32 v[10:11], v[210:211], v[10:11], v[212:213]
	v_pk_fma_f32 v[12:13], v[118:119], v[174:175], v[12:13]
	v_pk_fma_f32 v[10:11], v[116:117], v[176:177], v[10:11]
	global_store_dwordx4 v[152:153], v[10:13], off offset:64
	global_load_dwordx4 v[10:13], v[20:21], off offset:512
	v_mov_b32_e32 v118, 0
	v_mov_b32_e32 v116, 1.0
	s_cbranch_vccnz .LBB0_1832
	global_load_dwordx4 v[170:173], v[16:17], off offset:512
	global_load_dwordx4 v[174:177], v[14:15], off offset:512
	s_waitcnt vmcnt(1)
	v_pk_mul_f32 v[122:123], v[172:173], s[28:29] op_sel_hi:[1,0]
	v_pk_mul_f32 v[126:127], v[170:171], s[28:29] op_sel_hi:[1,0]
	s_waitcnt vmcnt(0)
	v_pk_mul_f32 v[130:131], v[176:177], s[28:29] op_sel_hi:[1,0]
	v_pk_mul_f32 v[134:135], v[174:175], s[28:29] op_sel_hi:[1,0]
.LBB0_1832:
	global_load_dwordx4 v[170:173], v[28:29], off offset:512
	global_load_dwordx4 v[180:183], v[32:33], off offset:512
	global_load_dwordx4 v[214:217], v[38:39], off offset:512
	global_load_dwordx4 v[218:221], v[48:49], off offset:512
	global_load_dwordx4 v[222:225], v[168:169], off offset:512
	s_waitcnt vmcnt(5)
	v_pk_add_f32 v[12:13], v[12:13], 1.0 op_sel_hi:[1,0]
	v_pk_add_f32 v[10:11], v[10:11], 1.0 op_sel_hi:[1,0]
	v_pk_mul_f32 v[138:139], v[12:13], 0.5 op_sel_hi:[1,0]
	v_pk_mul_f32 v[142:143], v[10:11], 0.5 op_sel_hi:[1,0]
	s_and_b64 vcc, exec, s[40:41]
	v_mov_b32_e32 v117, 1.0
	v_mov_b32_e32 v119, 0
	s_waitcnt vmcnt(4)
	v_sub_f32_e32 v11, v171, v0
	v_sub_f32_e32 v10, v170, v0
	v_sub_f32_e32 v13, v173, v0
	v_sub_f32_e32 v12, v172, v0
	v_pk_mul_f32 v[12:13], v[148:149], v[12:13]
	v_pk_mul_f32 v[10:11], v[8:9], v[10:11]
	v_pk_fma_f32 v[12:13], v[122:123], v[12:13], v[130:131]
	v_pk_fma_f32 v[10:11], v[126:127], v[10:11], v[134:135]
	v_pk_fma_f32 v[12:13], v[114:115], v[138:139], v[12:13]
	v_pk_fma_f32 v[10:11], v[112:113], v[142:143], v[10:11]
	global_store_dwordx4 v[30:31], v[10:13], off offset:512
	s_nop 1
	s_waitcnt vmcnt(4)
	v_sub_f32_e32 v11, v181, v1
	v_sub_f32_e32 v10, v180, v1
	v_sub_f32_e32 v13, v183, v1
	v_sub_f32_e32 v12, v182, v1
	v_pk_mul_f32 v[12:13], v[144:145], v[12:13]
	v_pk_mul_f32 v[10:11], v[202:203], v[10:11]
	v_pk_fma_f32 v[12:13], v[122:123], v[12:13], v[130:131]
	v_pk_fma_f32 v[10:11], v[126:127], v[10:11], v[134:135]
	v_pk_fma_f32 v[12:13], v[110:111], v[138:139], v[12:13]
	v_pk_fma_f32 v[10:11], v[108:109], v[142:143], v[10:11]
	global_store_dwordx4 v[34:35], v[10:13], off offset:512
	global_load_dwordx4 v[180:183], v[166:167], off offset:512
	s_waitcnt vmcnt(5)
	v_sub_f32_e32 v11, v215, v2
	v_sub_f32_e32 v10, v214, v2
	v_sub_f32_e32 v13, v217, v2
	v_sub_f32_e32 v12, v216, v2
	v_pk_mul_f32 v[12:13], v[140:141], v[12:13]
	v_pk_mul_f32 v[10:11], v[206:207], v[10:11]
	v_pk_fma_f32 v[12:13], v[122:123], v[12:13], v[130:131]
	v_pk_fma_f32 v[10:11], v[126:127], v[10:11], v[134:135]
	v_pk_fma_f32 v[12:13], v[106:107], v[138:139], v[12:13]
	v_pk_fma_f32 v[10:11], v[104:105], v[142:143], v[10:11]
	global_store_dwordx4 v[46:47], v[10:13], off offset:512
	global_load_dwordx4 v[214:217], v[162:163], off offset:512
	s_waitcnt vmcnt(6)
	v_sub_f32_e32 v11, v219, v3
	v_sub_f32_e32 v10, v218, v3
	v_sub_f32_e32 v13, v221, v3
	v_sub_f32_e32 v12, v220, v3
	v_pk_mul_f32 v[12:13], v[136:137], v[12:13]
	v_pk_mul_f32 v[10:11], v[204:205], v[10:11]
	v_pk_fma_f32 v[12:13], v[122:123], v[12:13], v[130:131]
	v_pk_fma_f32 v[10:11], v[126:127], v[10:11], v[134:135]
	v_pk_fma_f32 v[12:13], v[102:103], v[138:139], v[12:13]
	v_pk_fma_f32 v[10:11], v[100:101], v[142:143], v[10:11]
	global_store_dwordx4 v[40:41], v[10:13], off offset:512
	global_load_dwordx4 v[218:221], v[158:159], off offset:512
	s_waitcnt vmcnt(7)
	v_sub_f32_e32 v11, v223, v4
	v_sub_f32_e32 v10, v222, v4
	v_sub_f32_e32 v13, v225, v4
	v_sub_f32_e32 v12, v224, v4
	v_pk_mul_f32 v[12:13], v[132:133], v[12:13]
	v_pk_mul_f32 v[10:11], v[44:45], v[10:11]
	v_pk_fma_f32 v[12:13], v[122:123], v[12:13], v[130:131]
	v_pk_fma_f32 v[10:11], v[126:127], v[10:11], v[134:135]
	v_pk_fma_f32 v[12:13], v[98:99], v[138:139], v[12:13]
	v_pk_fma_f32 v[10:11], v[96:97], v[142:143], v[10:11]
	global_store_dwordx4 v[164:165], v[10:13], off offset:512
	s_nop 1
	s_waitcnt vmcnt(5)
	v_sub_f32_e32 v11, v181, v5
	v_sub_f32_e32 v10, v180, v5
	v_sub_f32_e32 v13, v183, v5
	v_sub_f32_e32 v12, v182, v5
	v_pk_mul_f32 v[12:13], v[128:129], v[12:13]
	v_pk_mul_f32 v[10:11], v[42:43], v[10:11]
	v_pk_fma_f32 v[12:13], v[122:123], v[12:13], v[130:131]
	v_pk_fma_f32 v[10:11], v[126:127], v[10:11], v[134:135]
	v_pk_fma_f32 v[12:13], v[94:95], v[138:139], v[12:13]
	v_pk_fma_f32 v[10:11], v[92:93], v[142:143], v[10:11]
	global_store_dwordx4 v[160:161], v[10:13], off offset:512
	s_nop 1
	s_waitcnt vmcnt(4)
	v_sub_f32_e32 v11, v215, v6
	v_sub_f32_e32 v10, v214, v6
	v_sub_f32_e32 v13, v217, v6
	v_sub_f32_e32 v12, v216, v6
	v_pk_mul_f32 v[12:13], v[124:125], v[12:13]
	v_pk_mul_f32 v[10:11], v[24:25], v[10:11]
	v_pk_fma_f32 v[12:13], v[122:123], v[12:13], v[130:131]
	v_pk_fma_f32 v[10:11], v[126:127], v[10:11], v[134:135]
	v_pk_fma_f32 v[12:13], v[90:91], v[138:139], v[12:13]
	v_pk_fma_f32 v[10:11], v[88:89], v[142:143], v[10:11]
	global_store_dwordx4 v[156:157], v[10:13], off offset:512
	s_nop 1
	s_waitcnt vmcnt(3)
	v_sub_f32_e32 v11, v219, v7
	v_sub_f32_e32 v10, v218, v7
	v_sub_f32_e32 v13, v221, v7
	v_sub_f32_e32 v12, v220, v7
	v_pk_mul_f32 v[12:13], v[120:121], v[12:13]
	v_pk_mul_f32 v[10:11], v[26:27], v[10:11]
	v_pk_fma_f32 v[12:13], v[122:123], v[12:13], v[130:131]
	v_pk_fma_f32 v[10:11], v[126:127], v[10:11], v[134:135]
	v_pk_fma_f32 v[12:13], v[86:87], v[138:139], v[12:13]
	v_pk_fma_f32 v[10:11], v[84:85], v[142:143], v[10:11]
	global_store_dwordx4 v[152:153], v[10:13], off offset:512
	global_load_dwordx4 v[10:13], v[20:21], off offset:576
	v_mov_b32_e32 v20, 1.0
	v_mov_b32_e32 v21, 1.0
	v_mov_b32_e32 v84, 0
	v_mov_b32_e32 v85, 0
	s_cbranch_vccnz .LBB0_1834
	global_load_dwordx4 v[84:87], v[16:17], off offset:576
	s_nop 0
	global_load_dwordx4 v[14:17], v[14:15], off offset:576
	s_waitcnt vmcnt(1)
	v_pk_mul_f32 v[20:21], v[86:87], s[28:29] op_sel_hi:[1,0]
	v_pk_mul_f32 v[116:117], v[84:85], s[28:29] op_sel_hi:[1,0]
	s_waitcnt vmcnt(0)
	v_pk_mul_f32 v[84:85], v[16:17], s[28:29] op_sel_hi:[1,0]
	v_pk_mul_f32 v[118:119], v[14:15], s[28:29] op_sel_hi:[1,0]
.LBB0_1834:
	global_load_dwordx4 v[14:17], v[28:29], off offset:576
	global_load_dwordx4 v[180:183], v[32:33], off offset:576
	global_load_dwordx4 v[214:217], v[38:39], off offset:576
	global_load_dwordx4 v[218:221], v[48:49], off offset:576
	global_load_dwordx4 v[222:225], v[168:169], off offset:576
	s_waitcnt vmcnt(5)
	v_pk_add_f32 v[10:11], v[10:11], 1.0 op_sel_hi:[1,0]
	v_mov_b32_e32 v28, v18
	v_mov_b32_e32 v29, v9
	v_pk_mul_f32 v[86:87], v[10:11], 0.5 op_sel_hi:[1,0]
	v_pk_add_f32 v[12:13], v[12:13], 1.0 op_sel_hi:[1,0]
	v_mov_b32_e32 v18, v202
	v_pk_mul_f32 v[12:13], v[12:13], 0.5 op_sel_hi:[1,0]
	s_and_b64 vcc, exec, s[38:39]
	s_mov_b64 s[26:27], -1
	s_waitcnt vmcnt(4)
	v_sub_f32_e32 v11, v15, v0
	v_sub_f32_e32 v10, v14, v0
	v_sub_f32_e32 v15, v17, v0
	v_sub_f32_e32 v14, v16, v0
	v_pk_mul_f32 v[14:15], v[28:29], v[14:15]
	v_pk_mul_f32 v[8:9], v[8:9], v[10:11]
	v_pk_fma_f32 v[10:11], v[20:21], v[14:15], v[84:85]
	v_pk_fma_f32 v[8:9], v[116:117], v[8:9], v[118:119]
	v_pk_fma_f32 v[10:11], v[82:83], v[12:13], v[10:11]
	v_pk_fma_f32 v[8:9], v[80:81], v[86:87], v[8:9]
	global_store_dwordx4 v[30:31], v[8:11], off offset:576
	s_nop 1
	s_waitcnt vmcnt(4)
	v_sub_f32_e32 v9, v181, v1
	v_sub_f32_e32 v8, v180, v1
	v_sub_f32_e32 v11, v183, v1
	v_sub_f32_e32 v10, v182, v1
	v_pk_mul_f32 v[0:1], v[18:19], v[10:11]
	v_pk_mul_f32 v[8:9], v[202:203], v[8:9]
	v_pk_fma_f32 v[0:1], v[20:21], v[0:1], v[84:85]
	v_pk_fma_f32 v[8:9], v[116:117], v[8:9], v[118:119]
	v_pk_fma_f32 v[10:11], v[78:79], v[12:13], v[0:1]
	v_pk_fma_f32 v[8:9], v[76:77], v[86:87], v[8:9]
	global_store_dwordx4 v[34:35], v[8:11], off offset:576
	global_load_dwordx4 v[180:183], v[166:167], off offset:576
	v_mov_b32_e32 v0, v22
	v_mov_b32_e32 v1, v207
	v_mov_b32_e32 v22, v204
	s_waitcnt vmcnt(5)
	v_sub_f32_e32 v9, v215, v2
	v_sub_f32_e32 v8, v214, v2
	v_sub_f32_e32 v11, v217, v2
	v_sub_f32_e32 v10, v216, v2
	v_pk_mul_f32 v[0:1], v[0:1], v[10:11]
	v_pk_mul_f32 v[8:9], v[206:207], v[8:9]
	v_pk_fma_f32 v[0:1], v[20:21], v[0:1], v[84:85]
	v_pk_fma_f32 v[8:9], v[116:117], v[8:9], v[118:119]
	v_pk_fma_f32 v[10:11], v[74:75], v[12:13], v[0:1]
	v_pk_fma_f32 v[8:9], v[72:73], v[86:87], v[8:9]
	global_store_dwordx4 v[46:47], v[8:11], off offset:576
	global_load_dwordx4 v[214:217], v[162:163], off offset:576
	s_waitcnt vmcnt(6)
	v_sub_f32_e32 v1, v219, v3
	v_sub_f32_e32 v0, v218, v3
	v_sub_f32_e32 v9, v221, v3
	v_sub_f32_e32 v8, v220, v3
	v_pk_mul_f32 v[2:3], v[22:23], v[8:9]
	v_pk_mul_f32 v[0:1], v[204:205], v[0:1]
	v_pk_fma_f32 v[2:3], v[20:21], v[2:3], v[84:85]
	v_pk_fma_f32 v[0:1], v[116:117], v[0:1], v[118:119]
	v_pk_fma_f32 v[2:3], v[70:71], v[12:13], v[2:3]
	v_pk_fma_f32 v[0:1], v[68:69], v[86:87], v[0:1]
	global_store_dwordx4 v[40:41], v[0:3], off offset:576
	global_load_dwordx4 v[218:221], v[158:159], off offset:576
	v_mov_b32_e32 v8, v36
	v_mov_b32_e32 v9, v45
	v_mov_b32_e32 v36, v42
	s_waitcnt vmcnt(7)
	v_sub_f32_e32 v1, v223, v4
	v_sub_f32_e32 v0, v222, v4
	v_sub_f32_e32 v3, v225, v4
	v_sub_f32_e32 v2, v224, v4
	v_pk_mul_f32 v[2:3], v[8:9], v[2:3]
	v_pk_mul_f32 v[0:1], v[44:45], v[0:1]
	v_pk_fma_f32 v[2:3], v[20:21], v[2:3], v[84:85]
	v_pk_fma_f32 v[0:1], v[116:117], v[0:1], v[118:119]
	v_pk_fma_f32 v[2:3], v[66:67], v[12:13], v[2:3]
	v_pk_fma_f32 v[0:1], v[64:65], v[86:87], v[0:1]
	global_store_dwordx4 v[164:165], v[0:3], off offset:576
	s_nop 1
	v_mov_b32_e32 v4, v24
	s_waitcnt vmcnt(5)
	v_sub_f32_e32 v1, v181, v5
	v_sub_f32_e32 v0, v180, v5
	v_sub_f32_e32 v3, v183, v5
	v_sub_f32_e32 v2, v182, v5
	v_pk_mul_f32 v[2:3], v[36:37], v[2:3]
	v_pk_mul_f32 v[0:1], v[42:43], v[0:1]
	v_pk_fma_f32 v[2:3], v[20:21], v[2:3], v[84:85]
	v_pk_fma_f32 v[0:1], v[116:117], v[0:1], v[118:119]
	v_pk_fma_f32 v[2:3], v[62:63], v[12:13], v[2:3]
	v_pk_fma_f32 v[0:1], v[60:61], v[86:87], v[0:1]
	global_store_dwordx4 v[160:161], v[0:3], off offset:576
	s_nop 1
	v_mov_b32_e32 v5, v24
	s_waitcnt vmcnt(4)
	v_sub_f32_e32 v1, v215, v6
	v_sub_f32_e32 v0, v214, v6
	v_sub_f32_e32 v3, v217, v6
	v_sub_f32_e32 v2, v216, v6
	v_pk_mul_f32 v[2:3], v[4:5], v[2:3]
	v_pk_mul_f32 v[0:1], v[24:25], v[0:1]
	v_pk_fma_f32 v[2:3], v[20:21], v[2:3], v[84:85]
	v_pk_fma_f32 v[0:1], v[116:117], v[0:1], v[118:119]
	v_pk_fma_f32 v[2:3], v[58:59], v[12:13], v[2:3]
	v_pk_fma_f32 v[0:1], v[56:57], v[86:87], v[0:1]
	global_store_dwordx4 v[156:157], v[0:3], off offset:576
	s_nop 1
	v_mov_b32_e32 v4, v26
	v_mov_b32_e32 v5, v26
	s_waitcnt vmcnt(3)
	v_sub_f32_e32 v1, v219, v7
	v_sub_f32_e32 v0, v218, v7
	v_sub_f32_e32 v3, v221, v7
	v_sub_f32_e32 v2, v220, v7
	v_pk_mul_f32 v[2:3], v[4:5], v[2:3]
	v_pk_mul_f32 v[0:1], v[26:27], v[0:1]
	v_pk_fma_f32 v[2:3], v[20:21], v[2:3], v[84:85]
	v_pk_fma_f32 v[0:1], v[116:117], v[0:1], v[118:119]
	v_pk_fma_f32 v[2:3], v[54:55], v[12:13], v[2:3]
	v_pk_fma_f32 v[0:1], v[52:53], v[86:87], v[0:1]
	global_store_dwordx4 v[152:153], v[0:3], off offset:576
	s_cbranch_vccnz .LBB0_1794
	s_andn2_b64 vcc, exec, s[2:3]
	s_cbranch_vccnz .LBB0_1793
	s_barrier
	s_branch .LBB0_1793
